# v25 + grid barrier: XCD leaders stop bumping / waiting on the unused per-XCD relay word
# speedup vs baseline: 1.0111x; 1.0005x over previous
.LBB0_114:
	s_or_b64 exec, exec, s[0:1]
	v_mov_b32_e32 v0, s23
	v_add_co_u32_e32 v0, vcc, 0x2000, v0
	v_mov_b32_e32 v1, s22
	s_nop 0
	v_addc_co_u32_e32 v1, vcc, 0, v1, vcc
	v_mov_b32_e32 v2, 1
	s_waitcnt vmcnt(1) lgkmcnt(0)

.LBB0_117:
	s_or_b64 exec, exec, s[4:5]
	v_mov_b32_e32 v0, s39
	v_add_co_u32_e32 v0, vcc, 0x2000, v0
	v_mov_b32_e32 v1, s38
	s_nop 0
	v_addc_co_u32_e32 v1, vcc, 0, v1, vcc
	s_waitcnt vmcnt(1) lgkmcnt(0)

.LBB0_265:
	s_or_b64 exec, exec, s[4:5]
	v_mov_b32_e32 v0, s19
	v_add_co_u32_e32 v0, vcc, 0x2000, v0
	v_mov_b32_e32 v1, s17
	s_nop 0
	v_addc_co_u32_e32 v1, vcc, 0, v1, vcc
	s_waitcnt vmcnt(1) lgkmcnt(0)

.LBB0_543:
	s_or_b64 exec, exec, s[4:5]
	v_mov_b32_e32 v0, s18
	v_add_co_u32_e32 v0, vcc, 0x2000, v0
	v_mov_b32_e32 v1, s17
	s_nop 0
	v_addc_co_u32_e32 v1, vcc, 0, v1, vcc
	s_waitcnt vmcnt(1) lgkmcnt(0)
